# v41 + epilogue sub-LN gain loads issued at tile-loop exit, ahead of the extra barrier and LDS exchange
# baseline (speedup 1.0000x reference)
.LBB0_1612:
	global_load_dwordx4 v[152:155], v162, s[38:39] offset:32
	global_load_dwordx4 v[156:159], v162, s[38:39] offset:64
	global_load_dwordx4 v[168:171], v162, s[38:39] offset:96
	global_load_dwordx4 v[172:175], v162, s[38:39] offset:128
	global_load_dwordx4 v[176:179], v162, s[38:39] offset:160
	global_load_dwordx4 v[180:183], v162, s[38:39] offset:192
	global_load_dwordx4 v[184:187], v162, s[38:39] offset:224
	global_load_dwordx4 v[188:191], v162, s[38:39] offset:256
	global_load_dwordx4 v[192:195], v162, s[38:39] offset:288
	global_load_dwordx4 v[196:199], v162, s[38:39] offset:320
	s_barrier
	s_setprio 0
	ds_bpermute_b32 v0, v163, v210
	s_cmp_lg_u32 s24, 1
	s_waitcnt lgkmcnt(0)
	v_add_f32_e32 v0, v210, v0
	v_div_scale_f32 v2, s[4:5], v0, v0, 1.0
	v_rcp_f32_e32 v3, v2
	v_div_scale_f32 v4, vcc, 1.0, v0, 1.0
	v_fma_f32 v5, -v2, v3, 1.0
	v_fmac_f32_e32 v3, v5, v3
	v_mul_f32_e32 v5, v4, v3
	v_fma_f32 v6, -v2, v5, v4
	v_fmac_f32_e32 v5, v6, v3
	v_fma_f32 v2, -v2, v5, v4
	v_div_fmas_f32 v2, v2, v3, v5
	v_div_fixup_f32 v0, v2, v0, 1.0
	s_cbranch_scc1 .LBB0_1614
	s_lshl_b32 s1, s1, 14
	s_add_i32 s1, s1, 0
	v_mul_f32_e32 v2, v64, v0
	v_lshl_add_u32 v3, v207, 2, s1
	v_mul_f32_e32 v4, v65, v0
	ds_write2st64_b32 v3, v2, v4 offset1:1
	v_mul_f32_e32 v2, v66, v0
	v_mul_f32_e32 v4, v67, v0
	ds_write2st64_b32 v3, v2, v4 offset0:2 offset1:3
	v_mul_f32_e32 v2, v68, v0
	v_mul_f32_e32 v4, v69, v0
	ds_write2st64_b32 v3, v2, v4 offset0:4 offset1:5
	v_mul_f32_e32 v2, v70, v0
	v_mul_f32_e32 v4, v71, v0
	ds_write2st64_b32 v3, v2, v4 offset0:6 offset1:7
	v_mul_f32_e32 v2, v72, v0
	v_mul_f32_e32 v4, v73, v0
	ds_write2st64_b32 v3, v2, v4 offset0:8 offset1:9
	v_mul_f32_e32 v2, v74, v0
	v_mul_f32_e32 v4, v75, v0
	ds_write2st64_b32 v3, v2, v4 offset0:10 offset1:11
	v_mul_f32_e32 v2, v76, v0
	v_mul_f32_e32 v4, v77, v0
	ds_write2st64_b32 v3, v2, v4 offset0:12 offset1:13
	v_mul_f32_e32 v2, v78, v0
	v_mul_f32_e32 v4, v79, v0
	ds_write2st64_b32 v3, v2, v4 offset0:14 offset1:15
	v_mul_f32_e32 v2, v48, v0
	v_mul_f32_e32 v4, v49, v0
	ds_write2st64_b32 v3, v2, v4 offset0:16 offset1:17
	v_mul_f32_e32 v2, v50, v0
	v_mul_f32_e32 v4, v51, v0
	ds_write2st64_b32 v3, v2, v4 offset0:18 offset1:19
	v_mul_f32_e32 v2, v52, v0
	v_mul_f32_e32 v4, v53, v0
	ds_write2st64_b32 v3, v2, v4 offset0:20 offset1:21
	v_mul_f32_e32 v2, v54, v0
	v_mul_f32_e32 v4, v55, v0
	ds_write2st64_b32 v3, v2, v4 offset0:22 offset1:23
	v_mul_f32_e32 v2, v56, v0
	v_mul_f32_e32 v4, v57, v0
	ds_write2st64_b32 v3, v2, v4 offset0:24 offset1:25
	v_mul_f32_e32 v2, v58, v0
	v_mul_f32_e32 v4, v59, v0
	ds_write2st64_b32 v3, v2, v4 offset0:26 offset1:27
	v_mul_f32_e32 v2, v60, v0
	v_mul_f32_e32 v4, v61, v0
	ds_write2st64_b32 v3, v2, v4 offset0:28 offset1:29
	v_mul_f32_e32 v2, v62, v0
	v_mul_f32_e32 v4, v63, v0
	ds_write2st64_b32 v3, v2, v4 offset0:30 offset1:31
	v_mul_f32_e32 v2, v32, v0
	v_mul_f32_e32 v4, v33, v0
	ds_write2st64_b32 v3, v2, v4 offset0:32 offset1:33
	v_mul_f32_e32 v2, v34, v0
	v_mul_f32_e32 v4, v35, v0
	ds_write2st64_b32 v3, v2, v4 offset0:34 offset1:35
	v_mul_f32_e32 v2, v36, v0
	v_mul_f32_e32 v4, v37, v0
	ds_write2st64_b32 v3, v2, v4 offset0:36 offset1:37
	v_mul_f32_e32 v2, v38, v0
	v_mul_f32_e32 v4, v39, v0
	ds_write2st64_b32 v3, v2, v4 offset0:38 offset1:39
	v_mul_f32_e32 v2, v40, v0
	v_mul_f32_e32 v4, v41, v0
	ds_write2st64_b32 v3, v2, v4 offset0:40 offset1:41
	v_mul_f32_e32 v2, v42, v0
	v_mul_f32_e32 v4, v43, v0
	ds_write2st64_b32 v3, v2, v4 offset0:42 offset1:43
	v_mul_f32_e32 v2, v44, v0
	v_mul_f32_e32 v4, v45, v0
	ds_write2st64_b32 v3, v2, v4 offset0:44 offset1:45
	v_mul_f32_e32 v2, v46, v0
	v_mul_f32_e32 v4, v47, v0
	ds_write2st64_b32 v3, v2, v4 offset0:46 offset1:47
	v_mul_f32_e32 v2, v16, v0
	v_mul_f32_e32 v4, v17, v0
	ds_write2st64_b32 v3, v2, v4 offset0:48 offset1:49
	v_mul_f32_e32 v2, v18, v0
	v_mul_f32_e32 v4, v19, v0
	ds_write2st64_b32 v3, v2, v4 offset0:50 offset1:51
	v_mul_f32_e32 v2, v20, v0
	v_mul_f32_e32 v4, v21, v0
	ds_write2st64_b32 v3, v2, v4 offset0:52 offset1:53
	v_mul_f32_e32 v2, v22, v0
	v_mul_f32_e32 v4, v23, v0
	ds_write2st64_b32 v3, v2, v4 offset0:54 offset1:55
	v_mul_f32_e32 v2, v24, v0
	v_mul_f32_e32 v4, v25, v0
	ds_write2st64_b32 v3, v2, v4 offset0:56 offset1:57
	v_mul_f32_e32 v2, v26, v0
	v_mul_f32_e32 v4, v27, v0
	ds_write2st64_b32 v3, v2, v4 offset0:58 offset1:59
	v_mul_f32_e32 v2, v28, v0
	v_mul_f32_e32 v4, v29, v0
	ds_write2st64_b32 v3, v2, v4 offset0:60 offset1:61
	v_mul_f32_e32 v2, v30, v0
	v_mul_f32_e32 v4, v31, v0
	ds_write2st64_b32 v3, v2, v4 offset0:62 offset1:63
.LBB0_1614:
	s_cmpk_gt_u32 s0, 0xff
	s_waitcnt lgkmcnt(0)
	s_barrier
	s_cbranch_scc1 .LBB0_1595
	s_lshl_b32 s0, s0, 8
	v_lshl_add_u32 v5, v207, 2, 0
	s_and_b32 s1, s0, 0xc000
	v_add_u32_e32 v6, s1, v5
	ds_read2st64_b32 v[10:11], v6 offset1:1
	ds_read2st64_b32 v[14:15], v6 offset0:2 offset1:3
	ds_read2st64_b32 v[86:87], v6 offset0:4 offset1:5
	ds_read2st64_b32 v[88:89], v6 offset0:6 offset1:7
	ds_read2st64_b32 v[90:91], v6 offset0:8 offset1:9
	ds_read2st64_b32 v[92:93], v6 offset0:10 offset1:11
	ds_read2st64_b32 v[94:95], v6 offset0:12 offset1:13
	ds_read2st64_b32 v[96:97], v6 offset0:14 offset1:15
	ds_read2st64_b32 v[98:99], v6 offset0:16 offset1:17
	ds_read2st64_b32 v[100:101], v6 offset0:18 offset1:19
	ds_read2st64_b32 v[102:103], v6 offset0:20 offset1:21
	ds_read2st64_b32 v[104:105], v6 offset0:22 offset1:23
	ds_read2st64_b32 v[106:107], v6 offset0:24 offset1:25
	ds_read2st64_b32 v[108:109], v6 offset0:26 offset1:27
	ds_read2st64_b32 v[110:111], v6 offset0:28 offset1:29
	ds_read2st64_b32 v[112:113], v6 offset0:30 offset1:31
	ds_read2st64_b32 v[114:115], v6 offset0:32 offset1:33
	ds_read2st64_b32 v[116:117], v6 offset0:34 offset1:35
	ds_read2st64_b32 v[118:119], v6 offset0:36 offset1:37
	ds_read2st64_b32 v[120:121], v6 offset0:38 offset1:39
	ds_read2st64_b32 v[122:123], v6 offset0:40 offset1:41
	ds_read2st64_b32 v[124:125], v6 offset0:42 offset1:43
	ds_read2st64_b32 v[126:127], v6 offset0:44 offset1:45
	ds_read2st64_b32 v[128:129], v6 offset0:46 offset1:47
	ds_read2st64_b32 v[12:13], v6 offset0:56 offset1:57
	ds_read2st64_b32 v[130:131], v6 offset0:58 offset1:59
	ds_read2st64_b32 v[2:3], v6 offset0:60 offset1:61
	ds_read_b32 v4, v6 offset:15872
	s_waitcnt lgkmcnt(14)
	v_pk_mul_f32 v[10:11], v[160:161], v[10:11]
	s_or_b32 s0, s0, 0x3f00
	v_pk_fma_f32 v[82:83], v[64:65], v[0:1], v[10:11] op_sel_hi:[1,0,1] neg_lo:[0,0,1] neg_hi:[0,0,1]
	v_pk_mul_f32 v[10:11], v[160:161], v[88:89]
	v_add_u32_e32 v5, s0, v5
	v_pk_fma_f32 v[70:71], v[70:71], v[0:1], v[10:11] op_sel_hi:[1,0,1] neg_lo:[0,0,1] neg_hi:[0,0,1]
	v_pk_mul_f32 v[10:11], v[160:161], v[86:87]
	ds_read_b32 v5, v5
	ds_read2st64_b32 v[132:133], v6 offset0:48 offset1:49
	ds_read2st64_b32 v[134:135], v6 offset0:50 offset1:51
	ds_read2st64_b32 v[136:137], v6 offset0:52 offset1:53
	ds_read2st64_b32 v[138:139], v6 offset0:54 offset1:55
	v_pk_fma_f32 v[86:87], v[68:69], v[0:1], v[10:11] op_sel_hi:[1,0,1] neg_lo:[0,0,1] neg_hi:[0,0,1]
	v_pk_mul_f32 v[10:11], v[160:161], v[92:93]
	s_waitcnt lgkmcnt(6)
	v_pk_mul_f32 v[2:3], v[160:161], v[2:3]
	v_pk_fma_f32 v[74:75], v[74:75], v[0:1], v[10:11] op_sel_hi:[1,0,1] neg_lo:[0,0,1] neg_hi:[0,0,1]
	v_pk_mul_f32 v[10:11], v[160:161], v[90:91]
	v_pk_fma_f32 v[6:7], v[28:29], v[0:1], v[2:3] op_sel_hi:[1,0,1] neg_lo:[0,0,1] neg_hi:[0,0,1]
	v_pk_fma_f32 v[90:91], v[72:73], v[0:1], v[10:11] op_sel_hi:[1,0,1] neg_lo:[0,0,1] neg_hi:[0,0,1]
	v_pk_mul_f32 v[10:11], v[160:161], v[96:97]
	s_waitcnt lgkmcnt(4)
	v_pk_mul_f32 v[2:3], v[160:161], v[4:5]
	v_pk_fma_f32 v[68:69], v[78:79], v[0:1], v[10:11] op_sel_hi:[1,0,1] neg_lo:[0,0,1] neg_hi:[0,0,1]
	v_pk_mul_f32 v[10:11], v[160:161], v[94:95]
	v_pk_fma_f32 v[8:9], v[30:31], v[0:1], v[2:3] op_sel_hi:[1,0,1] neg_lo:[0,0,1] neg_hi:[0,0,1]
	v_pk_fma_f32 v[88:89], v[76:77], v[0:1], v[10:11] op_sel_hi:[1,0,1] neg_lo:[0,0,1] neg_hi:[0,0,1]
	v_pk_mul_f32 v[10:11], v[160:161], v[100:101]
	v_pk_mul_f32 v[14:15], v[160:161], v[14:15]
	v_pk_fma_f32 v[64:65], v[50:51], v[0:1], v[10:11] op_sel_hi:[1,0,1] neg_lo:[0,0,1] neg_hi:[0,0,1]
	v_pk_mul_f32 v[10:11], v[160:161], v[98:99]
	v_pk_fma_f32 v[66:67], v[66:67], v[0:1], v[14:15] op_sel_hi:[1,0,1] neg_lo:[0,0,1] neg_hi:[0,0,1]
	v_pk_fma_f32 v[78:79], v[48:49], v[0:1], v[10:11] op_sel_hi:[1,0,1] neg_lo:[0,0,1] neg_hi:[0,0,1]
	v_pk_mul_f32 v[10:11], v[160:161], v[104:105]
	v_pk_mul_f32 v[142:143], v[82:83], v[82:83]
	v_pk_fma_f32 v[54:55], v[54:55], v[0:1], v[10:11] op_sel_hi:[1,0,1] neg_lo:[0,0,1] neg_hi:[0,0,1]
	v_pk_mul_f32 v[10:11], v[160:161], v[102:103]
	v_pk_mul_f32 v[12:13], v[160:161], v[12:13]
	v_pk_fma_f32 v[76:77], v[52:53], v[0:1], v[10:11] op_sel_hi:[1,0,1] neg_lo:[0,0,1] neg_hi:[0,0,1]
	v_pk_mul_f32 v[10:11], v[160:161], v[108:109]
	global_load_dwordx4 v[2:5], v162, s[38:39]
	v_pk_fma_f32 v[52:53], v[58:59], v[0:1], v[10:11] op_sel_hi:[1,0,1] neg_lo:[0,0,1] neg_hi:[0,0,1]
	v_pk_mul_f32 v[10:11], v[160:161], v[106:107]
	v_pk_mul_f32 v[140:141], v[66:67], v[66:67]
	v_pk_fma_f32 v[72:73], v[56:57], v[0:1], v[10:11] op_sel_hi:[1,0,1] neg_lo:[0,0,1] neg_hi:[0,0,1]
	v_pk_mul_f32 v[10:11], v[160:161], v[112:113]
	v_pk_fma_f32 v[12:13], v[24:25], v[0:1], v[12:13] op_sel_hi:[1,0,1] neg_lo:[0,0,1] neg_hi:[0,0,1]
	v_pk_fma_f32 v[50:51], v[62:63], v[0:1], v[10:11] op_sel_hi:[1,0,1] neg_lo:[0,0,1] neg_hi:[0,0,1]
	v_pk_mul_f32 v[10:11], v[160:161], v[110:111]
	v_pk_mul_f32 v[146:147], v[86:87], v[86:87]
	v_pk_fma_f32 v[60:61], v[60:61], v[0:1], v[10:11] op_sel_hi:[1,0,1] neg_lo:[0,0,1] neg_hi:[0,0,1]
	v_pk_mul_f32 v[10:11], v[160:161], v[116:117]
	v_pk_mul_f32 v[144:145], v[70:71], v[70:71]
	v_pk_fma_f32 v[48:49], v[34:35], v[0:1], v[10:11] op_sel_hi:[1,0,1] neg_lo:[0,0,1] neg_hi:[0,0,1]
	v_pk_mul_f32 v[10:11], v[160:161], v[114:115]
	v_pk_mul_f32 v[148:149], v[90:91], v[90:91]
	v_pk_fma_f32 v[58:59], v[32:33], v[0:1], v[10:11] op_sel_hi:[1,0,1] neg_lo:[0,0,1] neg_hi:[0,0,1]
	v_pk_mul_f32 v[10:11], v[160:161], v[120:121]
	v_pk_mul_f32 v[92:93], v[74:75], v[74:75]
	v_pk_fma_f32 v[32:33], v[38:39], v[0:1], v[10:11] op_sel_hi:[1,0,1] neg_lo:[0,0,1] neg_hi:[0,0,1]
	v_pk_mul_f32 v[10:11], v[160:161], v[118:119]
	v_pk_mul_f32 v[94:95], v[88:89], v[88:89]
	v_pk_fma_f32 v[56:57], v[36:37], v[0:1], v[10:11] op_sel_hi:[1,0,1] neg_lo:[0,0,1] neg_hi:[0,0,1]
	v_pk_mul_f32 v[10:11], v[160:161], v[124:125]
	v_pk_mul_f32 v[96:97], v[68:69], v[68:69]
	v_pk_fma_f32 v[30:31], v[42:43], v[0:1], v[10:11] op_sel_hi:[1,0,1] neg_lo:[0,0,1] neg_hi:[0,0,1]
	v_pk_mul_f32 v[10:11], v[160:161], v[122:123]
	v_pk_mul_f32 v[98:99], v[78:79], v[78:79]
	v_pk_fma_f32 v[38:39], v[40:41], v[0:1], v[10:11] op_sel_hi:[1,0,1] neg_lo:[0,0,1] neg_hi:[0,0,1]
	v_pk_mul_f32 v[10:11], v[160:161], v[128:129]
	v_pk_mul_f32 v[100:101], v[64:65], v[64:65]
	v_pk_fma_f32 v[28:29], v[46:47], v[0:1], v[10:11] op_sel_hi:[1,0,1] neg_lo:[0,0,1] neg_hi:[0,0,1]
	v_pk_mul_f32 v[10:11], v[160:161], v[126:127]
	v_pk_mul_f32 v[102:103], v[76:77], v[76:77]
	v_pk_fma_f32 v[36:37], v[44:45], v[0:1], v[10:11] op_sel_hi:[1,0,1] neg_lo:[0,0,1] neg_hi:[0,0,1]
	s_waitcnt lgkmcnt(2)
	v_pk_mul_f32 v[10:11], v[160:161], v[134:135]
	v_pk_mul_f32 v[104:105], v[54:55], v[54:55]
	v_pk_fma_f32 v[18:19], v[18:19], v[0:1], v[10:11] op_sel_hi:[1,0,1] neg_lo:[0,0,1] neg_hi:[0,0,1]
	v_pk_mul_f32 v[10:11], v[160:161], v[132:133]
	v_pk_mul_f32 v[106:107], v[72:73], v[72:73]
	v_pk_fma_f32 v[34:35], v[16:17], v[0:1], v[10:11] op_sel_hi:[1,0,1] neg_lo:[0,0,1] neg_hi:[0,0,1]
	s_waitcnt lgkmcnt(0)
	v_pk_mul_f32 v[10:11], v[160:161], v[138:139]
	v_pk_mul_f32 v[108:109], v[52:53], v[52:53]
	v_pk_fma_f32 v[14:15], v[22:23], v[0:1], v[10:11] op_sel_hi:[1,0,1] neg_lo:[0,0,1] neg_hi:[0,0,1]
	v_pk_mul_f32 v[10:11], v[160:161], v[136:137]
	v_pk_mul_f32 v[110:111], v[60:61], v[60:61]
	v_pk_fma_f32 v[16:17], v[20:21], v[0:1], v[10:11] op_sel_hi:[1,0,1] neg_lo:[0,0,1] neg_hi:[0,0,1]
	v_pk_mul_f32 v[10:11], v[160:161], v[130:131]
	v_pk_mul_f32 v[62:63], v[50:51], v[50:51]
	v_pk_fma_f32 v[10:11], v[26:27], v[0:1], v[10:11] op_sel_hi:[1,0,1] neg_lo:[0,0,1] neg_hi:[0,0,1]
	v_add_f32_e32 v0, v142, v143
	v_add_f32_e32 v0, v0, v140
	v_add_f32_e32 v0, v0, v141
	v_add_f32_e32 v0, v0, v146
	v_add_f32_e32 v0, v0, v147
	v_add_f32_e32 v0, v0, v144
	v_add_f32_e32 v0, v0, v145
	v_add_f32_e32 v0, v0, v148
	v_add_f32_e32 v0, v0, v149
	v_add_f32_e32 v0, v0, v92
	v_add_f32_e32 v0, v0, v93
	v_add_f32_e32 v0, v0, v94
	v_add_f32_e32 v0, v0, v95
	v_add_f32_e32 v0, v0, v96
	v_add_f32_e32 v0, v0, v97
	v_add_f32_e32 v0, v0, v98
	v_add_f32_e32 v0, v0, v99
	v_add_f32_e32 v0, v0, v100
	v_add_f32_e32 v0, v0, v101
	v_add_f32_e32 v0, v0, v102
	v_add_f32_e32 v0, v0, v103
	v_add_f32_e32 v0, v0, v104
	v_add_f32_e32 v0, v0, v105
	v_add_f32_e32 v0, v0, v106
	v_add_f32_e32 v0, v0, v107
	v_add_f32_e32 v0, v0, v108
	v_add_f32_e32 v0, v0, v109
	v_add_f32_e32 v0, v0, v110
	v_add_f32_e32 v0, v0, v111
	v_add_f32_e32 v0, v0, v62
	v_pk_mul_f32 v[114:115], v[58:59], v[58:59]
	v_add_f32_e32 v0, v0, v63
	v_add_f32_e32 v0, v0, v114
	v_pk_mul_f32 v[112:113], v[48:49], v[48:49]
	v_add_f32_e32 v0, v0, v115
	v_add_f32_e32 v0, v0, v112
	v_pk_mul_f32 v[118:119], v[56:57], v[56:57]
	v_add_f32_e32 v0, v0, v113
	v_add_f32_e32 v0, v0, v118
	v_pk_mul_f32 v[116:117], v[32:33], v[32:33]
	v_add_f32_e32 v0, v0, v119
	v_add_f32_e32 v0, v0, v116
	v_pk_mul_f32 v[40:41], v[38:39], v[38:39]
	v_add_f32_e32 v0, v0, v117
	v_add_f32_e32 v0, v0, v40
	v_pk_mul_f32 v[42:43], v[30:31], v[30:31]
	v_add_f32_e32 v0, v0, v41
	v_add_f32_e32 v0, v0, v42
	v_pk_mul_f32 v[44:45], v[36:37], v[36:37]
	v_add_f32_e32 v0, v0, v43
	v_add_f32_e32 v0, v0, v44
	v_pk_mul_f32 v[46:47], v[28:29], v[28:29]
	v_add_f32_e32 v0, v0, v45
	v_add_f32_e32 v0, v0, v46
	v_pk_mul_f32 v[122:123], v[34:35], v[34:35]
	v_add_f32_e32 v0, v0, v47
	v_add_f32_e32 v0, v0, v122
	v_pk_mul_f32 v[120:121], v[18:19], v[18:19]
	v_add_f32_e32 v0, v0, v123
	v_add_f32_e32 v0, v0, v120
	v_pk_mul_f32 v[20:21], v[16:17], v[16:17]
	v_add_f32_e32 v0, v0, v121
	v_add_f32_e32 v0, v0, v20
	v_pk_mul_f32 v[22:23], v[14:15], v[14:15]
	v_add_f32_e32 v0, v0, v21
	v_add_f32_e32 v0, v0, v22
	v_pk_mul_f32 v[24:25], v[12:13], v[12:13]
	v_add_f32_e32 v0, v0, v23
	v_add_f32_e32 v0, v0, v24
	v_pk_mul_f32 v[26:27], v[10:11], v[10:11]
	v_add_f32_e32 v0, v0, v25
	v_add_f32_e32 v0, v0, v26
	v_pk_mul_f32 v[80:81], v[6:7], v[6:7]
	v_add_f32_e32 v0, v0, v27
	v_add_f32_e32 v0, v0, v80
	v_pk_mul_f32 v[84:85], v[8:9], v[8:9]
	v_add_f32_e32 v0, v0, v81
	v_add_f32_e32 v0, v0, v84
	v_add_f32_e32 v22, v0, v85
	ds_bpermute_b32 v23, v163, v22
	v_lshlrev_b32_e32 v0, 1, v164
	v_lshl_add_u64 v[20:21], s[46:47], 0, v[0:1]
	v_lshl_add_u64 v[20:21], v[20:21], 0, v[166:167]
	s_mov_b64 s[0:1], 0x80
	s_waitcnt lgkmcnt(0)
	v_add_f32_e32 v0, v22, v23
	v_fmamk_f32 v0, v0, 0x3c000000, v205
	v_mul_f32_e32 v22, 0x4b800000, v0
	v_cmp_gt_f32_e32 vcc, s58, v0
	s_nop 1
	v_cndmask_b32_e32 v0, v0, v22, vcc
	v_rsq_f32_e32 v22, v0
	v_lshlrev_b32_e32 v0, 3, v165
	v_lshl_add_u64 v[20:21], v[20:21], 0, v[0:1]
	v_mul_f32_e32 v0, 0x45800000, v22
	v_cndmask_b32_e32 v0, v22, v0, vcc
	v_mul_f32_e32 v0, 0x3f077f5a, v0
	v_pk_mul_f32 v[22:23], v[82:83], v[0:1] op_sel_hi:[1,0]
	v_pk_mul_f32 v[24:25], v[86:87], v[0:1] op_sel_hi:[1,0]
	s_waitcnt vmcnt(0)
	v_pk_mul_f32 v[2:3], v[2:3], v[22:23]
	v_pk_mul_f32 v[22:23], v[66:67], v[0:1] op_sel_hi:[1,0]
	v_cvt_pk_bf16_f32 v2, v2, v3
	v_pk_mul_f32 v[4:5], v[4:5], v[22:23]
	v_lshl_add_u64 v[22:23], v[20:21], 0, 16
	v_cvt_pk_bf16_f32 v3, v4, v5
	global_store_dwordx2 v[20:21], v[2:3], off sc1
	s_nop 1
	v_mov_b64_e32 v[2:3], v[152:153]
	v_mov_b64_e32 v[4:5], v[154:155]
	v_pk_mul_f32 v[26:27], v[74:75], v[0:1] op_sel_hi:[1,0]
	v_pk_mul_f32 v[18:19], v[18:19], v[0:1] op_sel_hi:[1,0]
	v_pk_mul_f32 v[16:17], v[16:17], v[0:1] op_sel_hi:[1,0]
	v_pk_mul_f32 v[14:15], v[14:15], v[0:1] op_sel_hi:[1,0]
	v_pk_mul_f32 v[12:13], v[12:13], v[0:1] op_sel_hi:[1,0]
	v_pk_mul_f32 v[10:11], v[10:11], v[0:1] op_sel_hi:[1,0]
	v_pk_mul_f32 v[6:7], v[6:7], v[0:1] op_sel_hi:[1,0]
	v_pk_mul_f32 v[8:9], v[8:9], v[0:1] op_sel_hi:[1,0]
	v_pk_mul_f32 v[2:3], v[2:3], v[24:25]
	v_pk_mul_f32 v[24:25], v[70:71], v[0:1] op_sel_hi:[1,0]
	v_cvt_pk_bf16_f32 v2, v2, v3
	v_pk_mul_f32 v[4:5], v[4:5], v[24:25]
	v_pk_mul_f32 v[24:25], v[90:91], v[0:1] op_sel_hi:[1,0]
	v_cvt_pk_bf16_f32 v3, v4, v5
	global_store_dwordx2 v[22:23], v[2:3], off sc1
	s_nop 1
	v_mov_b64_e32 v[2:3], v[156:157]
	v_mov_b64_e32 v[4:5], v[158:159]
	v_lshl_add_u64 v[22:23], v[20:21], 0, 32
	v_pk_mul_f32 v[2:3], v[2:3], v[24:25]
	v_pk_mul_f32 v[4:5], v[4:5], v[26:27]
	v_cvt_pk_bf16_f32 v2, v2, v3
	v_cvt_pk_bf16_f32 v3, v4, v5
	global_store_dwordx2 v[22:23], v[2:3], off sc1
	s_nop 1
	v_mov_b64_e32 v[2:3], v[168:169]
	v_mov_b64_e32 v[4:5], v[170:171]
	v_pk_mul_f32 v[24:25], v[88:89], v[0:1] op_sel_hi:[1,0]
	v_pk_mul_f32 v[26:27], v[68:69], v[0:1] op_sel_hi:[1,0]
	v_lshl_add_u64 v[22:23], v[20:21], 0, 48
	v_pk_mul_f32 v[2:3], v[2:3], v[24:25]
	v_pk_mul_f32 v[4:5], v[4:5], v[26:27]
	v_cvt_pk_bf16_f32 v2, v2, v3
	v_cvt_pk_bf16_f32 v3, v4, v5
	global_store_dwordx2 v[22:23], v[2:3], off sc1
	s_nop 1
	v_mov_b64_e32 v[2:3], v[172:173]
	v_mov_b64_e32 v[4:5], v[174:175]
	v_pk_mul_f32 v[24:25], v[78:79], v[0:1] op_sel_hi:[1,0]
	v_pk_mul_f32 v[26:27], v[64:65], v[0:1] op_sel_hi:[1,0]
	v_lshl_add_u64 v[22:23], v[20:21], 0, 64
	v_pk_mul_f32 v[2:3], v[2:3], v[24:25]
	v_pk_mul_f32 v[4:5], v[4:5], v[26:27]
	v_cvt_pk_bf16_f32 v2, v2, v3
	v_cvt_pk_bf16_f32 v3, v4, v5
	global_store_dwordx2 v[22:23], v[2:3], off sc1
	s_nop 1
	v_mov_b64_e32 v[2:3], v[176:177]
	v_mov_b64_e32 v[4:5], v[178:179]
	global_load_dwordx4 v[152:155], v162, s[38:39] offset:352
	global_load_dwordx4 v[156:159], v162, s[38:39] offset:384
	global_load_dwordx4 v[168:171], v162, s[38:39] offset:416
	global_load_dwordx4 v[172:175], v162, s[38:39] offset:448
	global_load_dwordx4 v[176:179], v162, s[38:39] offset:480
	v_pk_mul_f32 v[24:25], v[76:77], v[0:1] op_sel_hi:[1,0]
	v_pk_mul_f32 v[26:27], v[54:55], v[0:1] op_sel_hi:[1,0]
	v_lshl_add_u64 v[22:23], v[20:21], 0, s[42:43]
	v_pk_mul_f32 v[2:3], v[2:3], v[24:25]
	v_pk_mul_f32 v[4:5], v[4:5], v[26:27]
	v_cvt_pk_bf16_f32 v2, v2, v3
	v_cvt_pk_bf16_f32 v3, v4, v5
	global_store_dwordx2 v[22:23], v[2:3], off sc1
	s_nop 1
	v_mov_b64_e32 v[2:3], v[180:181]
	v_mov_b64_e32 v[4:5], v[182:183]
	v_pk_mul_f32 v[24:25], v[72:73], v[0:1] op_sel_hi:[1,0]
	v_pk_mul_f32 v[26:27], v[52:53], v[0:1] op_sel_hi:[1,0]
	v_lshl_add_u64 v[22:23], v[20:21], 0, s[44:45]
	v_pk_mul_f32 v[2:3], v[2:3], v[24:25]
	v_pk_mul_f32 v[4:5], v[4:5], v[26:27]
	v_cvt_pk_bf16_f32 v2, v2, v3
	v_cvt_pk_bf16_f32 v3, v4, v5
	global_store_dwordx2 v[22:23], v[2:3], off sc1
	s_nop 1
	v_mov_b64_e32 v[2:3], v[184:185]
	v_mov_b64_e32 v[4:5], v[186:187]
	v_pk_mul_f32 v[24:25], v[60:61], v[0:1] op_sel_hi:[1,0]
	v_pk_mul_f32 v[26:27], v[50:51], v[0:1] op_sel_hi:[1,0]
	v_lshl_add_u64 v[22:23], v[20:21], 0, s[52:53]
	v_pk_mul_f32 v[2:3], v[24:25], v[2:3]
	v_pk_mul_f32 v[4:5], v[26:27], v[4:5]
	v_cvt_pk_bf16_f32 v2, v2, v3
	v_cvt_pk_bf16_f32 v3, v4, v5
	global_store_dwordx2 v[22:23], v[2:3], off sc1
	s_nop 1
	v_mov_b64_e32 v[2:3], v[188:189]
	v_mov_b64_e32 v[4:5], v[190:191]
	v_pk_mul_f32 v[24:25], v[58:59], v[0:1] op_sel_hi:[1,0]
	v_pk_mul_f32 v[26:27], v[48:49], v[0:1] op_sel_hi:[1,0]
	v_lshl_add_u64 v[22:23], v[20:21], 0, s[0:1]
	s_mov_b64 s[0:1], 0x90
	v_pk_mul_f32 v[2:3], v[24:25], v[2:3]
	v_pk_mul_f32 v[4:5], v[26:27], v[4:5]
	v_cvt_pk_bf16_f32 v2, v2, v3
	v_cvt_pk_bf16_f32 v3, v4, v5
	global_store_dwordx2 v[22:23], v[2:3], off sc1
	s_nop 1
	v_mov_b64_e32 v[2:3], v[192:193]
	v_mov_b64_e32 v[4:5], v[194:195]
	v_pk_mul_f32 v[24:25], v[56:57], v[0:1] op_sel_hi:[1,0]
	v_pk_mul_f32 v[26:27], v[32:33], v[0:1] op_sel_hi:[1,0]
	v_lshl_add_u64 v[22:23], v[20:21], 0, s[0:1]
	s_mov_b64 s[0:1], 0xa0
	v_pk_mul_f32 v[2:3], v[24:25], v[2:3]
	v_pk_mul_f32 v[4:5], v[26:27], v[4:5]
	v_cvt_pk_bf16_f32 v2, v2, v3
	v_cvt_pk_bf16_f32 v3, v4, v5
	global_store_dwordx2 v[22:23], v[2:3], off sc1
	s_nop 1
	v_mov_b64_e32 v[2:3], v[196:197]
	v_mov_b64_e32 v[4:5], v[198:199]
	v_pk_mul_f32 v[24:25], v[38:39], v[0:1] op_sel_hi:[1,0]
	v_pk_mul_f32 v[26:27], v[30:31], v[0:1] op_sel_hi:[1,0]
	v_lshl_add_u64 v[22:23], v[20:21], 0, s[0:1]
	s_mov_b64 s[0:1], 0xb0
	v_pk_mul_f32 v[2:3], v[24:25], v[2:3]
	v_pk_mul_f32 v[4:5], v[26:27], v[4:5]
	v_cvt_pk_bf16_f32 v2, v2, v3
	v_cvt_pk_bf16_f32 v3, v4, v5
	global_store_dwordx2 v[22:23], v[2:3], off sc1
	s_nop 1
	s_waitcnt vmcnt(6)
	v_mov_b64_e32 v[2:3], v[152:153]
	v_mov_b64_e32 v[4:5], v[154:155]
	v_pk_mul_f32 v[24:25], v[36:37], v[0:1] op_sel_hi:[1,0]
	v_pk_mul_f32 v[26:27], v[28:29], v[0:1] op_sel_hi:[1,0]
	v_lshl_add_u64 v[22:23], v[20:21], 0, s[0:1]
	s_mov_b64 s[0:1], 0xc0
	v_pk_mul_f32 v[2:3], v[24:25], v[2:3]
	v_pk_mul_f32 v[4:5], v[26:27], v[4:5]
	v_cvt_pk_bf16_f32 v2, v2, v3
	v_cvt_pk_bf16_f32 v3, v4, v5
	global_store_dwordx2 v[22:23], v[2:3], off sc1
	s_nop 1
	v_mov_b64_e32 v[2:3], v[156:157]
	v_mov_b64_e32 v[4:5], v[158:159]
	v_pk_mul_f32 v[24:25], v[34:35], v[0:1] op_sel_hi:[1,0]
	v_lshl_add_u64 v[22:23], v[20:21], 0, s[0:1]
	s_mov_b64 s[0:1], 0xd0
	v_pk_mul_f32 v[2:3], v[24:25], v[2:3]
	v_pk_mul_f32 v[4:5], v[18:19], v[4:5]
	v_cvt_pk_bf16_f32 v2, v2, v3
	v_cvt_pk_bf16_f32 v3, v4, v5
	global_store_dwordx2 v[22:23], v[2:3], off sc1
	s_nop 1
	v_mov_b64_e32 v[2:3], v[168:169]
	v_mov_b64_e32 v[4:5], v[170:171]
	v_lshl_add_u64 v[18:19], v[20:21], 0, s[0:1]
	s_mov_b64 s[0:1], 0xe0
	v_pk_mul_f32 v[2:3], v[16:17], v[2:3]
	v_pk_mul_f32 v[4:5], v[14:15], v[4:5]
	v_cvt_pk_bf16_f32 v2, v2, v3
	v_cvt_pk_bf16_f32 v3, v4, v5
	global_store_dwordx2 v[18:19], v[2:3], off sc1
	s_nop 1
	v_mov_b64_e32 v[2:3], v[172:173]
	v_mov_b64_e32 v[4:5], v[174:175]
	v_lshl_add_u64 v[14:15], v[20:21], 0, s[0:1]
	s_mov_b64 s[0:1], 0xf0
	v_pk_mul_f32 v[2:3], v[12:13], v[2:3]
	v_pk_mul_f32 v[4:5], v[10:11], v[4:5]
	v_cvt_pk_bf16_f32 v2, v2, v3
	v_cvt_pk_bf16_f32 v3, v4, v5
	global_store_dwordx2 v[14:15], v[2:3], off sc1
	s_nop 1
	v_mov_b64_e32 v[2:3], v[176:177]
	v_mov_b64_e32 v[4:5], v[178:179]
	v_pk_mul_f32 v[2:3], v[6:7], v[2:3]
	v_pk_mul_f32 v[4:5], v[8:9], v[4:5]
	v_cvt_pk_bf16_f32 v2, v2, v3
	v_cvt_pk_bf16_f32 v3, v4, v5
	v_lshl_add_u64 v[4:5], v[20:21], 0, s[0:1]
	global_store_dwordx2 v[4:5], v[2:3], off sc1
	s_nop 1
	s_branch .LBB0_1595

.LBB0_2165:
	global_load_dwordx4 v[152:155], v164, s[38:39] offset:544
	global_load_dwordx4 v[156:159], v164, s[38:39] offset:576
	global_load_dwordx4 v[168:171], v164, s[38:39] offset:608
	global_load_dwordx4 v[172:175], v164, s[38:39] offset:640
	global_load_dwordx4 v[176:179], v164, s[38:39] offset:672
	global_load_dwordx4 v[180:183], v164, s[38:39] offset:704
	global_load_dwordx4 v[184:187], v164, s[38:39] offset:736
	global_load_dwordx4 v[188:191], v164, s[38:39] offset:768
	global_load_dwordx4 v[192:195], v164, s[38:39] offset:800
	global_load_dwordx4 v[196:199], v164, s[38:39] offset:832
	s_barrier
	s_setprio 0
	ds_bpermute_b32 v0, v165, v210
	s_cmp_lg_u32 s12, 1
	s_waitcnt lgkmcnt(0)
	v_add_f32_e32 v0, v210, v0
	v_div_scale_f32 v2, s[4:5], v0, v0, 1.0
	v_rcp_f32_e32 v3, v2
	v_div_scale_f32 v4, vcc, 1.0, v0, 1.0
	v_fma_f32 v5, -v2, v3, 1.0
	v_fmac_f32_e32 v3, v5, v3
	v_mul_f32_e32 v5, v4, v3
	v_fma_f32 v6, -v2, v5, v4
	v_fmac_f32_e32 v5, v6, v3
	v_fma_f32 v2, -v2, v5, v4
	v_div_fmas_f32 v2, v2, v3, v5
	v_div_fixup_f32 v0, v2, v0, 1.0
	s_cbranch_scc1 .LBB0_2167
	s_lshl_b32 s1, s1, 14
	s_add_i32 s1, s1, 0
	v_mul_f32_e32 v2, v64, v0
	v_lshl_add_u32 v3, v207, 2, s1
	v_mul_f32_e32 v4, v65, v0
	ds_write2st64_b32 v3, v2, v4 offset1:1
	v_mul_f32_e32 v2, v66, v0
	v_mul_f32_e32 v4, v67, v0
	ds_write2st64_b32 v3, v2, v4 offset0:2 offset1:3
	v_mul_f32_e32 v2, v68, v0
	v_mul_f32_e32 v4, v69, v0
	ds_write2st64_b32 v3, v2, v4 offset0:4 offset1:5
	v_mul_f32_e32 v2, v70, v0
	v_mul_f32_e32 v4, v71, v0
	ds_write2st64_b32 v3, v2, v4 offset0:6 offset1:7
	v_mul_f32_e32 v2, v72, v0
	v_mul_f32_e32 v4, v73, v0
	ds_write2st64_b32 v3, v2, v4 offset0:8 offset1:9
	v_mul_f32_e32 v2, v74, v0
	v_mul_f32_e32 v4, v75, v0
	ds_write2st64_b32 v3, v2, v4 offset0:10 offset1:11
	v_mul_f32_e32 v2, v76, v0
	v_mul_f32_e32 v4, v77, v0
	ds_write2st64_b32 v3, v2, v4 offset0:12 offset1:13
	v_mul_f32_e32 v2, v78, v0
	v_mul_f32_e32 v4, v79, v0
	ds_write2st64_b32 v3, v2, v4 offset0:14 offset1:15
	v_mul_f32_e32 v2, v48, v0
	v_mul_f32_e32 v4, v49, v0
	ds_write2st64_b32 v3, v2, v4 offset0:16 offset1:17
	v_mul_f32_e32 v2, v50, v0
	v_mul_f32_e32 v4, v51, v0
	ds_write2st64_b32 v3, v2, v4 offset0:18 offset1:19
	v_mul_f32_e32 v2, v52, v0
	v_mul_f32_e32 v4, v53, v0
	ds_write2st64_b32 v3, v2, v4 offset0:20 offset1:21
	v_mul_f32_e32 v2, v54, v0
	v_mul_f32_e32 v4, v55, v0
	ds_write2st64_b32 v3, v2, v4 offset0:22 offset1:23
	v_mul_f32_e32 v2, v56, v0
	v_mul_f32_e32 v4, v57, v0
	ds_write2st64_b32 v3, v2, v4 offset0:24 offset1:25
	v_mul_f32_e32 v2, v58, v0
	v_mul_f32_e32 v4, v59, v0
	ds_write2st64_b32 v3, v2, v4 offset0:26 offset1:27
	v_mul_f32_e32 v2, v60, v0
	v_mul_f32_e32 v4, v61, v0
	ds_write2st64_b32 v3, v2, v4 offset0:28 offset1:29
	v_mul_f32_e32 v2, v62, v0
	v_mul_f32_e32 v4, v63, v0
	ds_write2st64_b32 v3, v2, v4 offset0:30 offset1:31
	v_mul_f32_e32 v2, v32, v0
	v_mul_f32_e32 v4, v33, v0
	ds_write2st64_b32 v3, v2, v4 offset0:32 offset1:33
	v_mul_f32_e32 v2, v34, v0
	v_mul_f32_e32 v4, v35, v0
	ds_write2st64_b32 v3, v2, v4 offset0:34 offset1:35
	v_mul_f32_e32 v2, v36, v0
	v_mul_f32_e32 v4, v37, v0
	ds_write2st64_b32 v3, v2, v4 offset0:36 offset1:37
	v_mul_f32_e32 v2, v38, v0
	v_mul_f32_e32 v4, v39, v0
	ds_write2st64_b32 v3, v2, v4 offset0:38 offset1:39
	v_mul_f32_e32 v2, v40, v0
	v_mul_f32_e32 v4, v41, v0
	ds_write2st64_b32 v3, v2, v4 offset0:40 offset1:41
	v_mul_f32_e32 v2, v42, v0
	v_mul_f32_e32 v4, v43, v0
	ds_write2st64_b32 v3, v2, v4 offset0:42 offset1:43
	v_mul_f32_e32 v2, v44, v0
	v_mul_f32_e32 v4, v45, v0
	ds_write2st64_b32 v3, v2, v4 offset0:44 offset1:45
	v_mul_f32_e32 v2, v46, v0
	v_mul_f32_e32 v4, v47, v0
	ds_write2st64_b32 v3, v2, v4 offset0:46 offset1:47
	v_mul_f32_e32 v2, v16, v0
	v_mul_f32_e32 v4, v17, v0
	ds_write2st64_b32 v3, v2, v4 offset0:48 offset1:49
	v_mul_f32_e32 v2, v18, v0
	v_mul_f32_e32 v4, v19, v0
	ds_write2st64_b32 v3, v2, v4 offset0:50 offset1:51
	v_mul_f32_e32 v2, v20, v0
	v_mul_f32_e32 v4, v21, v0
	ds_write2st64_b32 v3, v2, v4 offset0:52 offset1:53
	v_mul_f32_e32 v2, v22, v0
	v_mul_f32_e32 v4, v23, v0
	ds_write2st64_b32 v3, v2, v4 offset0:54 offset1:55
	v_mul_f32_e32 v2, v24, v0
	v_mul_f32_e32 v4, v25, v0
	ds_write2st64_b32 v3, v2, v4 offset0:56 offset1:57
	v_mul_f32_e32 v2, v26, v0
	v_mul_f32_e32 v4, v27, v0
	ds_write2st64_b32 v3, v2, v4 offset0:58 offset1:59
	v_mul_f32_e32 v2, v28, v0
	v_mul_f32_e32 v4, v29, v0
	ds_write2st64_b32 v3, v2, v4 offset0:60 offset1:61
	v_mul_f32_e32 v2, v30, v0
	v_mul_f32_e32 v4, v31, v0
	ds_write2st64_b32 v3, v2, v4 offset0:62 offset1:63
.LBB0_2167:
	s_cmpk_gt_u32 s0, 0xff
	s_waitcnt lgkmcnt(0)
	s_barrier
	s_cbranch_scc1 .LBB0_2148
	s_lshl_b32 s0, s0, 8
	v_lshl_add_u32 v5, v207, 2, 0
	s_and_b32 s1, s0, 0xc000
	v_add_u32_e32 v6, s1, v5
	ds_read2st64_b32 v[10:11], v6 offset1:1
	ds_read2st64_b32 v[14:15], v6 offset0:2 offset1:3
	ds_read2st64_b32 v[86:87], v6 offset0:4 offset1:5
	ds_read2st64_b32 v[88:89], v6 offset0:6 offset1:7
	ds_read2st64_b32 v[90:91], v6 offset0:8 offset1:9
	ds_read2st64_b32 v[92:93], v6 offset0:10 offset1:11
	ds_read2st64_b32 v[94:95], v6 offset0:12 offset1:13
	ds_read2st64_b32 v[96:97], v6 offset0:14 offset1:15
	ds_read2st64_b32 v[98:99], v6 offset0:16 offset1:17
	ds_read2st64_b32 v[100:101], v6 offset0:18 offset1:19
	ds_read2st64_b32 v[102:103], v6 offset0:20 offset1:21
	ds_read2st64_b32 v[104:105], v6 offset0:22 offset1:23
	ds_read2st64_b32 v[106:107], v6 offset0:24 offset1:25
	ds_read2st64_b32 v[108:109], v6 offset0:26 offset1:27
	ds_read2st64_b32 v[110:111], v6 offset0:28 offset1:29
	ds_read2st64_b32 v[112:113], v6 offset0:30 offset1:31
	ds_read2st64_b32 v[114:115], v6 offset0:32 offset1:33
	ds_read2st64_b32 v[116:117], v6 offset0:34 offset1:35
	ds_read2st64_b32 v[118:119], v6 offset0:36 offset1:37
	ds_read2st64_b32 v[120:121], v6 offset0:38 offset1:39
	ds_read2st64_b32 v[122:123], v6 offset0:40 offset1:41
	ds_read2st64_b32 v[124:125], v6 offset0:42 offset1:43
	ds_read2st64_b32 v[126:127], v6 offset0:44 offset1:45
	ds_read2st64_b32 v[128:129], v6 offset0:46 offset1:47
	ds_read2st64_b32 v[12:13], v6 offset0:56 offset1:57
	ds_read2st64_b32 v[130:131], v6 offset0:58 offset1:59
	ds_read2st64_b32 v[2:3], v6 offset0:60 offset1:61
	ds_read_b32 v4, v6 offset:15872
	s_waitcnt lgkmcnt(14)
	v_pk_mul_f32 v[10:11], v[160:161], v[10:11]
	s_or_b32 s0, s0, 0x3f00
	v_pk_fma_f32 v[82:83], v[64:65], v[0:1], v[10:11] op_sel_hi:[1,0,1] neg_lo:[0,0,1] neg_hi:[0,0,1]
	v_pk_mul_f32 v[10:11], v[160:161], v[88:89]
	v_add_u32_e32 v5, s0, v5
	v_pk_fma_f32 v[70:71], v[70:71], v[0:1], v[10:11] op_sel_hi:[1,0,1] neg_lo:[0,0,1] neg_hi:[0,0,1]
	v_pk_mul_f32 v[10:11], v[160:161], v[86:87]
	ds_read_b32 v5, v5
	ds_read2st64_b32 v[132:133], v6 offset0:48 offset1:49
	ds_read2st64_b32 v[134:135], v6 offset0:50 offset1:51
	ds_read2st64_b32 v[136:137], v6 offset0:52 offset1:53
	ds_read2st64_b32 v[138:139], v6 offset0:54 offset1:55
	v_pk_fma_f32 v[86:87], v[68:69], v[0:1], v[10:11] op_sel_hi:[1,0,1] neg_lo:[0,0,1] neg_hi:[0,0,1]
	v_pk_mul_f32 v[10:11], v[160:161], v[92:93]
	s_waitcnt lgkmcnt(6)
	v_pk_mul_f32 v[2:3], v[160:161], v[2:3]
	v_pk_fma_f32 v[74:75], v[74:75], v[0:1], v[10:11] op_sel_hi:[1,0,1] neg_lo:[0,0,1] neg_hi:[0,0,1]
	v_pk_mul_f32 v[10:11], v[160:161], v[90:91]
	v_pk_fma_f32 v[6:7], v[28:29], v[0:1], v[2:3] op_sel_hi:[1,0,1] neg_lo:[0,0,1] neg_hi:[0,0,1]
	v_pk_fma_f32 v[90:91], v[72:73], v[0:1], v[10:11] op_sel_hi:[1,0,1] neg_lo:[0,0,1] neg_hi:[0,0,1]
	v_pk_mul_f32 v[10:11], v[160:161], v[96:97]
	s_waitcnt lgkmcnt(4)
	v_pk_mul_f32 v[2:3], v[160:161], v[4:5]
	v_pk_fma_f32 v[68:69], v[78:79], v[0:1], v[10:11] op_sel_hi:[1,0,1] neg_lo:[0,0,1] neg_hi:[0,0,1]
	v_pk_mul_f32 v[10:11], v[160:161], v[94:95]
	v_pk_fma_f32 v[8:9], v[30:31], v[0:1], v[2:3] op_sel_hi:[1,0,1] neg_lo:[0,0,1] neg_hi:[0,0,1]
	v_pk_fma_f32 v[88:89], v[76:77], v[0:1], v[10:11] op_sel_hi:[1,0,1] neg_lo:[0,0,1] neg_hi:[0,0,1]
	v_pk_mul_f32 v[10:11], v[160:161], v[100:101]
	v_pk_mul_f32 v[14:15], v[160:161], v[14:15]
	v_pk_fma_f32 v[64:65], v[50:51], v[0:1], v[10:11] op_sel_hi:[1,0,1] neg_lo:[0,0,1] neg_hi:[0,0,1]
	v_pk_mul_f32 v[10:11], v[160:161], v[98:99]
	v_pk_fma_f32 v[66:67], v[66:67], v[0:1], v[14:15] op_sel_hi:[1,0,1] neg_lo:[0,0,1] neg_hi:[0,0,1]
	v_pk_fma_f32 v[78:79], v[48:49], v[0:1], v[10:11] op_sel_hi:[1,0,1] neg_lo:[0,0,1] neg_hi:[0,0,1]
	v_pk_mul_f32 v[10:11], v[160:161], v[104:105]
	v_pk_mul_f32 v[142:143], v[82:83], v[82:83]
	v_pk_fma_f32 v[54:55], v[54:55], v[0:1], v[10:11] op_sel_hi:[1,0,1] neg_lo:[0,0,1] neg_hi:[0,0,1]
	v_pk_mul_f32 v[10:11], v[160:161], v[102:103]
	v_pk_mul_f32 v[12:13], v[160:161], v[12:13]
	v_pk_fma_f32 v[76:77], v[52:53], v[0:1], v[10:11] op_sel_hi:[1,0,1] neg_lo:[0,0,1] neg_hi:[0,0,1]
	v_pk_mul_f32 v[10:11], v[160:161], v[108:109]
	global_load_dwordx4 v[2:5], v164, s[38:39] offset:512
	v_pk_fma_f32 v[50:51], v[58:59], v[0:1], v[10:11] op_sel_hi:[1,0,1] neg_lo:[0,0,1] neg_hi:[0,0,1]
	v_pk_mul_f32 v[10:11], v[160:161], v[106:107]
	v_pk_mul_f32 v[140:141], v[66:67], v[66:67]
	v_pk_fma_f32 v[72:73], v[56:57], v[0:1], v[10:11] op_sel_hi:[1,0,1] neg_lo:[0,0,1] neg_hi:[0,0,1]
	v_pk_mul_f32 v[10:11], v[160:161], v[112:113]
	v_pk_fma_f32 v[12:13], v[24:25], v[0:1], v[12:13] op_sel_hi:[1,0,1] neg_lo:[0,0,1] neg_hi:[0,0,1]
	v_pk_fma_f32 v[48:49], v[62:63], v[0:1], v[10:11] op_sel_hi:[1,0,1] neg_lo:[0,0,1] neg_hi:[0,0,1]
	v_pk_mul_f32 v[10:11], v[160:161], v[110:111]
	v_pk_mul_f32 v[146:147], v[86:87], v[86:87]
	v_pk_fma_f32 v[58:59], v[60:61], v[0:1], v[10:11] op_sel_hi:[1,0,1] neg_lo:[0,0,1] neg_hi:[0,0,1]
	v_pk_mul_f32 v[10:11], v[160:161], v[116:117]
	v_pk_mul_f32 v[144:145], v[70:71], v[70:71]
	v_pk_fma_f32 v[34:35], v[34:35], v[0:1], v[10:11] op_sel_hi:[1,0,1] neg_lo:[0,0,1] neg_hi:[0,0,1]
	v_pk_mul_f32 v[10:11], v[160:161], v[114:115]
	v_pk_mul_f32 v[148:149], v[90:91], v[90:91]
	v_pk_fma_f32 v[56:57], v[32:33], v[0:1], v[10:11] op_sel_hi:[1,0,1] neg_lo:[0,0,1] neg_hi:[0,0,1]
	v_pk_mul_f32 v[10:11], v[160:161], v[120:121]
	v_pk_mul_f32 v[92:93], v[74:75], v[74:75]
	v_pk_fma_f32 v[32:33], v[38:39], v[0:1], v[10:11] op_sel_hi:[1,0,1] neg_lo:[0,0,1] neg_hi:[0,0,1]
	v_pk_mul_f32 v[10:11], v[160:161], v[118:119]
	v_pk_mul_f32 v[94:95], v[88:89], v[88:89]
	v_pk_fma_f32 v[52:53], v[36:37], v[0:1], v[10:11] op_sel_hi:[1,0,1] neg_lo:[0,0,1] neg_hi:[0,0,1]
	v_pk_mul_f32 v[10:11], v[160:161], v[124:125]
	v_pk_mul_f32 v[96:97], v[68:69], v[68:69]
	v_pk_fma_f32 v[30:31], v[42:43], v[0:1], v[10:11] op_sel_hi:[1,0,1] neg_lo:[0,0,1] neg_hi:[0,0,1]
	v_pk_mul_f32 v[10:11], v[160:161], v[122:123]
	v_pk_mul_f32 v[98:99], v[78:79], v[78:79]
	v_pk_fma_f32 v[40:41], v[40:41], v[0:1], v[10:11] op_sel_hi:[1,0,1] neg_lo:[0,0,1] neg_hi:[0,0,1]
	v_pk_mul_f32 v[10:11], v[160:161], v[128:129]
	v_pk_mul_f32 v[100:101], v[64:65], v[64:65]
	v_pk_fma_f32 v[28:29], v[46:47], v[0:1], v[10:11] op_sel_hi:[1,0,1] neg_lo:[0,0,1] neg_hi:[0,0,1]
	v_pk_mul_f32 v[10:11], v[160:161], v[126:127]
	v_pk_mul_f32 v[102:103], v[76:77], v[76:77]
	v_pk_fma_f32 v[38:39], v[44:45], v[0:1], v[10:11] op_sel_hi:[1,0,1] neg_lo:[0,0,1] neg_hi:[0,0,1]
	s_waitcnt lgkmcnt(2)
	v_pk_mul_f32 v[10:11], v[160:161], v[134:135]
	v_pk_mul_f32 v[104:105], v[54:55], v[54:55]
	v_pk_fma_f32 v[18:19], v[18:19], v[0:1], v[10:11] op_sel_hi:[1,0,1] neg_lo:[0,0,1] neg_hi:[0,0,1]
	v_pk_mul_f32 v[10:11], v[160:161], v[132:133]
	v_pk_mul_f32 v[106:107], v[72:73], v[72:73]
	v_pk_fma_f32 v[36:37], v[16:17], v[0:1], v[10:11] op_sel_hi:[1,0,1] neg_lo:[0,0,1] neg_hi:[0,0,1]
	s_waitcnt lgkmcnt(0)
	v_pk_mul_f32 v[10:11], v[160:161], v[138:139]
	v_pk_mul_f32 v[108:109], v[50:51], v[50:51]
	v_pk_fma_f32 v[14:15], v[22:23], v[0:1], v[10:11] op_sel_hi:[1,0,1] neg_lo:[0,0,1] neg_hi:[0,0,1]
	v_pk_mul_f32 v[10:11], v[160:161], v[136:137]
	v_pk_mul_f32 v[60:61], v[58:59], v[58:59]
	v_pk_fma_f32 v[16:17], v[20:21], v[0:1], v[10:11] op_sel_hi:[1,0,1] neg_lo:[0,0,1] neg_hi:[0,0,1]
	v_pk_mul_f32 v[10:11], v[160:161], v[130:131]
	v_pk_mul_f32 v[62:63], v[48:49], v[48:49]
	v_pk_fma_f32 v[10:11], v[26:27], v[0:1], v[10:11] op_sel_hi:[1,0,1] neg_lo:[0,0,1] neg_hi:[0,0,1]
	v_add_f32_e32 v0, v142, v143
	v_add_f32_e32 v0, v0, v140
	v_add_f32_e32 v0, v0, v141
	v_add_f32_e32 v0, v0, v146
	v_add_f32_e32 v0, v0, v147
	v_add_f32_e32 v0, v0, v144
	v_add_f32_e32 v0, v0, v145
	v_add_f32_e32 v0, v0, v148
	v_add_f32_e32 v0, v0, v149
	v_add_f32_e32 v0, v0, v92
	v_add_f32_e32 v0, v0, v93
	v_add_f32_e32 v0, v0, v94
	v_add_f32_e32 v0, v0, v95
	v_add_f32_e32 v0, v0, v96
	v_add_f32_e32 v0, v0, v97
	v_add_f32_e32 v0, v0, v98
	v_add_f32_e32 v0, v0, v99
	v_add_f32_e32 v0, v0, v100
	v_add_f32_e32 v0, v0, v101
	v_add_f32_e32 v0, v0, v102
	v_add_f32_e32 v0, v0, v103
	v_add_f32_e32 v0, v0, v104
	v_add_f32_e32 v0, v0, v105
	v_add_f32_e32 v0, v0, v106
	v_add_f32_e32 v0, v0, v107
	v_add_f32_e32 v0, v0, v108
	v_add_f32_e32 v0, v0, v109
	v_add_f32_e32 v0, v0, v60
	v_add_f32_e32 v0, v0, v61
	v_add_f32_e32 v0, v0, v62
	v_pk_mul_f32 v[112:113], v[56:57], v[56:57]
	v_add_f32_e32 v0, v0, v63
	v_add_f32_e32 v0, v0, v112
	v_pk_mul_f32 v[110:111], v[34:35], v[34:35]
	v_add_f32_e32 v0, v0, v113
	v_add_f32_e32 v0, v0, v110
	v_pk_mul_f32 v[116:117], v[52:53], v[52:53]
	v_add_f32_e32 v0, v0, v111
	v_add_f32_e32 v0, v0, v116
	v_pk_mul_f32 v[114:115], v[32:33], v[32:33]
	v_add_f32_e32 v0, v0, v117
	v_add_f32_e32 v0, v0, v114
	v_pk_mul_f32 v[118:119], v[40:41], v[40:41]
	v_add_f32_e32 v0, v0, v115
	v_add_f32_e32 v0, v0, v118
	v_pk_mul_f32 v[42:43], v[30:31], v[30:31]
	v_add_f32_e32 v0, v0, v119
	v_add_f32_e32 v0, v0, v42
	v_pk_mul_f32 v[44:45], v[38:39], v[38:39]
	v_add_f32_e32 v0, v0, v43
	v_add_f32_e32 v0, v0, v44
	v_pk_mul_f32 v[46:47], v[28:29], v[28:29]
	v_add_f32_e32 v0, v0, v45
	v_add_f32_e32 v0, v0, v46
	v_pk_mul_f32 v[122:123], v[36:37], v[36:37]
	v_add_f32_e32 v0, v0, v47
	v_add_f32_e32 v0, v0, v122
	v_pk_mul_f32 v[120:121], v[18:19], v[18:19]
	v_add_f32_e32 v0, v0, v123
	v_add_f32_e32 v0, v0, v120
	v_pk_mul_f32 v[20:21], v[16:17], v[16:17]
	v_add_f32_e32 v0, v0, v121
	v_add_f32_e32 v0, v0, v20
	v_pk_mul_f32 v[22:23], v[14:15], v[14:15]
	v_add_f32_e32 v0, v0, v21
	v_add_f32_e32 v0, v0, v22
	v_pk_mul_f32 v[24:25], v[12:13], v[12:13]
	v_add_f32_e32 v0, v0, v23
	v_add_f32_e32 v0, v0, v24
	v_pk_mul_f32 v[26:27], v[10:11], v[10:11]
	v_add_f32_e32 v0, v0, v25
	v_add_f32_e32 v0, v0, v26
	v_pk_mul_f32 v[80:81], v[6:7], v[6:7]
	v_add_f32_e32 v0, v0, v27
	v_add_f32_e32 v0, v0, v80
	v_pk_mul_f32 v[84:85], v[8:9], v[8:9]
	v_add_f32_e32 v0, v0, v81
	v_add_f32_e32 v0, v0, v84
	v_add_f32_e32 v22, v0, v85
	ds_bpermute_b32 v23, v165, v22
	v_lshlrev_b32_e32 v0, 1, v162
	v_lshl_add_u64 v[20:21], s[46:47], 0, v[0:1]
	v_lshl_add_u64 v[20:21], v[20:21], 0, v[166:167]
	s_waitcnt lgkmcnt(0)
	v_add_f32_e32 v0, v22, v23
	v_fmamk_f32 v0, v0, 0x3c000000, v205
	v_mul_f32_e32 v22, 0x4b800000, v0
	v_cmp_gt_f32_e32 vcc, s65, v0
	s_nop 1
	v_cndmask_b32_e32 v0, v0, v22, vcc
	v_rsq_f32_e32 v22, v0
	v_lshlrev_b32_e32 v0, 3, v163
	v_lshl_add_u64 v[20:21], v[20:21], 0, v[0:1]
	v_mul_f32_e32 v0, 0x45800000, v22
	v_cndmask_b32_e32 v0, v22, v0, vcc
	v_mul_f32_e32 v0, 0x3ee34c56, v0
	v_pk_mul_f32 v[22:23], v[82:83], v[0:1] op_sel_hi:[1,0]
	v_pk_mul_f32 v[24:25], v[86:87], v[0:1] op_sel_hi:[1,0]
	s_waitcnt vmcnt(0)
	v_pk_mul_f32 v[2:3], v[2:3], v[22:23]
	v_pk_mul_f32 v[22:23], v[66:67], v[0:1] op_sel_hi:[1,0]
	v_cvt_pk_bf16_f32 v2, v2, v3
	v_pk_mul_f32 v[4:5], v[4:5], v[22:23]
	v_lshl_add_u64 v[22:23], v[20:21], 0, 16
	v_cvt_pk_bf16_f32 v3, v4, v5
	global_store_dwordx2 v[20:21], v[2:3], off sc1
	s_nop 1
	v_mov_b64_e32 v[2:3], v[152:153]
	v_mov_b64_e32 v[4:5], v[154:155]
	v_pk_mul_f32 v[26:27], v[74:75], v[0:1] op_sel_hi:[1,0]
	v_pk_mul_f32 v[18:19], v[18:19], v[0:1] op_sel_hi:[1,0]
	v_pk_mul_f32 v[16:17], v[16:17], v[0:1] op_sel_hi:[1,0]
	v_pk_mul_f32 v[14:15], v[14:15], v[0:1] op_sel_hi:[1,0]
	v_pk_mul_f32 v[12:13], v[12:13], v[0:1] op_sel_hi:[1,0]
	v_pk_mul_f32 v[10:11], v[10:11], v[0:1] op_sel_hi:[1,0]
	v_pk_mul_f32 v[6:7], v[6:7], v[0:1] op_sel_hi:[1,0]
	v_pk_mul_f32 v[8:9], v[8:9], v[0:1] op_sel_hi:[1,0]
	v_pk_mul_f32 v[2:3], v[2:3], v[24:25]
	v_pk_mul_f32 v[24:25], v[70:71], v[0:1] op_sel_hi:[1,0]
	v_cvt_pk_bf16_f32 v2, v2, v3
	v_pk_mul_f32 v[4:5], v[4:5], v[24:25]
	v_pk_mul_f32 v[24:25], v[90:91], v[0:1] op_sel_hi:[1,0]
	v_cvt_pk_bf16_f32 v3, v4, v5
	global_store_dwordx2 v[22:23], v[2:3], off sc1
	s_nop 1
	v_mov_b64_e32 v[2:3], v[156:157]
	v_mov_b64_e32 v[4:5], v[158:159]
	v_lshl_add_u64 v[22:23], v[20:21], 0, 32
	v_pk_mul_f32 v[2:3], v[2:3], v[24:25]
	v_pk_mul_f32 v[4:5], v[4:5], v[26:27]
	v_cvt_pk_bf16_f32 v2, v2, v3
	v_cvt_pk_bf16_f32 v3, v4, v5
	global_store_dwordx2 v[22:23], v[2:3], off sc1
	s_nop 1
	v_mov_b64_e32 v[2:3], v[168:169]
	v_mov_b64_e32 v[4:5], v[170:171]
	v_pk_mul_f32 v[24:25], v[88:89], v[0:1] op_sel_hi:[1,0]
	v_pk_mul_f32 v[26:27], v[68:69], v[0:1] op_sel_hi:[1,0]
	v_lshl_add_u64 v[22:23], v[20:21], 0, 48
	v_pk_mul_f32 v[2:3], v[2:3], v[24:25]
	v_pk_mul_f32 v[4:5], v[4:5], v[26:27]
	v_cvt_pk_bf16_f32 v2, v2, v3
	v_cvt_pk_bf16_f32 v3, v4, v5
	global_store_dwordx2 v[22:23], v[2:3], off sc1
	s_nop 1
	v_mov_b64_e32 v[2:3], v[172:173]
	v_mov_b64_e32 v[4:5], v[174:175]
	v_pk_mul_f32 v[24:25], v[78:79], v[0:1] op_sel_hi:[1,0]
	v_pk_mul_f32 v[26:27], v[64:65], v[0:1] op_sel_hi:[1,0]
	v_lshl_add_u64 v[22:23], v[20:21], 0, 64
	v_pk_mul_f32 v[2:3], v[2:3], v[24:25]
	v_pk_mul_f32 v[4:5], v[4:5], v[26:27]
	v_cvt_pk_bf16_f32 v2, v2, v3
	v_cvt_pk_bf16_f32 v3, v4, v5
	global_store_dwordx2 v[22:23], v[2:3], off sc1
	s_nop 1
	v_mov_b64_e32 v[2:3], v[176:177]
	v_mov_b64_e32 v[4:5], v[178:179]
	global_load_dwordx4 v[152:155], v164, s[38:39] offset:864
	global_load_dwordx4 v[156:159], v164, s[38:39] offset:896
	global_load_dwordx4 v[168:171], v164, s[38:39] offset:928
	global_load_dwordx4 v[172:175], v164, s[38:39] offset:960
	global_load_dwordx4 v[176:179], v164, s[38:39] offset:992
	v_pk_mul_f32 v[24:25], v[76:77], v[0:1] op_sel_hi:[1,0]
	v_pk_mul_f32 v[26:27], v[54:55], v[0:1] op_sel_hi:[1,0]
	v_lshl_add_u64 v[22:23], v[20:21], 0, s[28:29]
	v_pk_mul_f32 v[2:3], v[2:3], v[24:25]
	v_pk_mul_f32 v[4:5], v[4:5], v[26:27]
	v_cvt_pk_bf16_f32 v2, v2, v3
	v_cvt_pk_bf16_f32 v3, v4, v5
	global_store_dwordx2 v[22:23], v[2:3], off sc1
	s_nop 1
	v_mov_b64_e32 v[2:3], v[180:181]
	v_mov_b64_e32 v[4:5], v[182:183]
	v_pk_mul_f32 v[24:25], v[72:73], v[0:1] op_sel_hi:[1,0]
	v_pk_mul_f32 v[26:27], v[50:51], v[0:1] op_sel_hi:[1,0]
	v_lshl_add_u64 v[22:23], v[20:21], 0, s[36:37]
	v_pk_mul_f32 v[2:3], v[2:3], v[24:25]
	v_pk_mul_f32 v[4:5], v[4:5], v[26:27]
	v_cvt_pk_bf16_f32 v2, v2, v3
	v_cvt_pk_bf16_f32 v3, v4, v5
	global_store_dwordx2 v[22:23], v[2:3], off sc1
	s_nop 1
	v_mov_b64_e32 v[2:3], v[184:185]
	v_mov_b64_e32 v[4:5], v[186:187]
	v_pk_mul_f32 v[24:25], v[58:59], v[0:1] op_sel_hi:[1,0]
	v_pk_mul_f32 v[26:27], v[48:49], v[0:1] op_sel_hi:[1,0]
	v_lshl_add_u64 v[22:23], v[20:21], 0, s[40:41]
	v_pk_mul_f32 v[2:3], v[24:25], v[2:3]
	v_pk_mul_f32 v[4:5], v[26:27], v[4:5]
	v_cvt_pk_bf16_f32 v2, v2, v3
	v_cvt_pk_bf16_f32 v3, v4, v5
	global_store_dwordx2 v[22:23], v[2:3], off sc1
	s_nop 1
	v_mov_b64_e32 v[2:3], v[188:189]
	v_mov_b64_e32 v[4:5], v[190:191]
	v_pk_mul_f32 v[24:25], v[56:57], v[0:1] op_sel_hi:[1,0]
	v_pk_mul_f32 v[26:27], v[34:35], v[0:1] op_sel_hi:[1,0]
	v_lshl_add_u64 v[22:23], v[20:21], 0, s[52:53]
	v_pk_mul_f32 v[2:3], v[24:25], v[2:3]
	v_pk_mul_f32 v[4:5], v[26:27], v[4:5]
	v_cvt_pk_bf16_f32 v2, v2, v3
	v_cvt_pk_bf16_f32 v3, v4, v5
	global_store_dwordx2 v[22:23], v[2:3], off sc1
	s_nop 1
	v_mov_b64_e32 v[2:3], v[192:193]
	v_mov_b64_e32 v[4:5], v[194:195]
	v_pk_mul_f32 v[24:25], v[52:53], v[0:1] op_sel_hi:[1,0]
	v_pk_mul_f32 v[26:27], v[32:33], v[0:1] op_sel_hi:[1,0]
	v_lshl_add_u64 v[22:23], v[20:21], 0, s[54:55]
	v_pk_mul_f32 v[2:3], v[24:25], v[2:3]
	v_pk_mul_f32 v[4:5], v[26:27], v[4:5]
	v_cvt_pk_bf16_f32 v2, v2, v3
	v_cvt_pk_bf16_f32 v3, v4, v5
	global_store_dwordx2 v[22:23], v[2:3], off sc1
	s_nop 1
	v_mov_b64_e32 v[2:3], v[196:197]
	v_mov_b64_e32 v[4:5], v[198:199]
	v_pk_mul_f32 v[24:25], v[40:41], v[0:1] op_sel_hi:[1,0]
	v_pk_mul_f32 v[26:27], v[30:31], v[0:1] op_sel_hi:[1,0]
	v_lshl_add_u64 v[22:23], v[20:21], 0, s[56:57]
	v_pk_mul_f32 v[2:3], v[24:25], v[2:3]
	v_pk_mul_f32 v[4:5], v[26:27], v[4:5]
	v_cvt_pk_bf16_f32 v2, v2, v3
	v_cvt_pk_bf16_f32 v3, v4, v5
	global_store_dwordx2 v[22:23], v[2:3], off sc1
	s_nop 1
	s_waitcnt vmcnt(6)
	v_mov_b64_e32 v[2:3], v[152:153]
	v_mov_b64_e32 v[4:5], v[154:155]
	v_pk_mul_f32 v[24:25], v[38:39], v[0:1] op_sel_hi:[1,0]
	v_pk_mul_f32 v[26:27], v[28:29], v[0:1] op_sel_hi:[1,0]
	v_lshl_add_u64 v[22:23], v[20:21], 0, s[58:59]
	v_pk_mul_f32 v[2:3], v[24:25], v[2:3]
	v_pk_mul_f32 v[4:5], v[26:27], v[4:5]
	v_cvt_pk_bf16_f32 v2, v2, v3
	v_cvt_pk_bf16_f32 v3, v4, v5
	global_store_dwordx2 v[22:23], v[2:3], off sc1
	s_nop 1
	v_mov_b64_e32 v[2:3], v[156:157]
	v_mov_b64_e32 v[4:5], v[158:159]
	v_pk_mul_f32 v[24:25], v[36:37], v[0:1] op_sel_hi:[1,0]
	v_lshl_add_u64 v[22:23], v[20:21], 0, s[70:71]
	v_pk_mul_f32 v[2:3], v[24:25], v[2:3]
	v_pk_mul_f32 v[4:5], v[18:19], v[4:5]
	v_cvt_pk_bf16_f32 v2, v2, v3
	v_cvt_pk_bf16_f32 v3, v4, v5
	global_store_dwordx2 v[22:23], v[2:3], off sc1
	s_nop 1
	v_mov_b64_e32 v[2:3], v[168:169]
	v_mov_b64_e32 v[4:5], v[170:171]
	v_lshl_add_u64 v[18:19], v[20:21], 0, s[72:73]
	v_pk_mul_f32 v[2:3], v[16:17], v[2:3]
	v_pk_mul_f32 v[4:5], v[14:15], v[4:5]
	v_cvt_pk_bf16_f32 v2, v2, v3
	v_cvt_pk_bf16_f32 v3, v4, v5
	global_store_dwordx2 v[18:19], v[2:3], off sc1
	s_nop 1
	v_mov_b64_e32 v[2:3], v[172:173]
	v_mov_b64_e32 v[4:5], v[174:175]
	v_lshl_add_u64 v[14:15], v[20:21], 0, s[74:75]
	v_pk_mul_f32 v[2:3], v[12:13], v[2:3]
	v_pk_mul_f32 v[4:5], v[10:11], v[4:5]
	v_cvt_pk_bf16_f32 v2, v2, v3
	v_cvt_pk_bf16_f32 v3, v4, v5
	global_store_dwordx2 v[14:15], v[2:3], off sc1
	s_nop 1
	v_mov_b64_e32 v[2:3], v[176:177]
	v_mov_b64_e32 v[4:5], v[178:179]
	v_pk_mul_f32 v[2:3], v[6:7], v[2:3]
	v_pk_mul_f32 v[4:5], v[8:9], v[4:5]
	v_cvt_pk_bf16_f32 v2, v2, v3
	v_cvt_pk_bf16_f32 v3, v4, v5
	v_lshl_add_u64 v[4:5], v[20:21], 0, s[76:77]
	global_store_dwordx2 v[4:5], v[2:3], off sc1
	s_nop 1
	s_branch .LBB0_2148
